# hand-written FFN-up epilogue: A rows permuted at staging so conv3 neighbours are in-lane registers (DPP only across lanes), ds_read_b64 weights, fewer VALU ops
# speedup vs baseline: 1.0159x; 1.0159x over previous
; #define PG8_STAGE(bufoff, soff, R, voff) do { _Pragma("unroll") for (int _i = 0; _i < 2; ++_i) \
;         __builtin_amdgcn_raw_ptr_buffer_load_lds(R, (LAS unsigned*)(lds + (bufoff) + ldsw + _i * 8192), 16, (int)(voff)[_i], (int)(soff), 0, 0); } while (0)
; __device__ __forceinline__ void gemm_phase(LAS unsigned char* lds, const GemmD& g, const EpiG& E) {
;     ...
;     for (int i = 0; i < 2; ++i) { int R, C; stage_rc(tid * 16 + i * 8192, R, C); const int Rb = E.perm() ? ((R & ~31) + perm32(R & 31)) : R;
;         voffA[i] = (unsigned)(R * g.lda + C) * 2u; voffB[i] = (unsigned)(Rb * g.ldb + C) * 2u; }
;     const __amdgpu_buffer_rsrc_t rA = __builtin_amdgcn_make_buffer_rsrc((void*)g.A, (short)0, 0x7fffffff, 0x00020000);
;     const __amdgpu_buffer_rsrc_t rB = __builtin_amdgcn_make_buffer_rsrc((void*)g.Bt, (short)0, 0x7fffffff, 0x00020000);
;     const unsigned kstep = (unsigned)(BK * 2);
;     const unsigned hstepA = (unsigned)HALF * g.lda * 2, hstepB = (unsigned)HALF * g.ldb * 2;
;     ...
;     unsigned cA = (unsigned)cur.pm * tstepA;
;     unsigned cB = (unsigned)(((size_t)(cur.pm / g.tilesPerBatch) * g.bBatchStride) * 2) + (unsigned)cur.pn * tstepB;
;     PG8_STAGE(PG8_SB(0, 0), cB, rB, voffB); PG8_STAGE(PG8_SA(0, 0), cA, rA, voffA); PG8_STAGE(PG8_SB(0, 1), cB + hstepB, rB, voffB); PG8_STAGE(PG8_SA(0, 1), cA + hstepA, rA, voffA);
.LBB0_322:
	s_andn2_b64 vcc, exec, s[4:5]
	s_cbranch_vccnz .LBB0_387
	v_readlane_b32 s1, v255, 8
	v_mov_b32_e32 v8, 1
	s_sub_i32 s5, 0, s40
	v_lshl_add_u32 v2, v1, 4, s1
	v_ashrrev_i32_e32 v3, 31, v2
	v_lshrrev_b32_e32 v3, 22, v3
	v_add_u32_e32 v3, v2, v3
	v_ashrrev_i32_e32 v3, 10, v3
	v_mul_i32_i24_e32 v4, 0x400, v3
	v_sub_u32_e32 v4, v2, v4
	v_lshrrev_b32_e32 v5, 4, v4
	v_bitop3_b32 v4, v5, v4, 32 bitop3:0x6c
	v_ashrrev_i32_e32 v6, 31, v4
	v_lshrrev_b32_e32 v6, 26, v6
	v_add_u32_e32 v6, v4, v6
	v_lshlrev_b32_e32 v5, 3, v3
	v_ashrrev_i32_e32 v7, 6, v6
	v_and_b32_e32 v6, 0xc0, v6
	v_and_b32_e32 v5, -16, v5
	v_lshlrev_b32_e32 v3, 5, v3
	v_sub_u32_e32 v4, v4, v6
	v_add_u32_e32 v5, v7, v5
	v_and_b32_e32 v3, 32, v3
	v_ashrrev_i16_sdwa v4, v8, sext(v4) dst_sel:DWORD dst_unused:UNUSED_PAD src0_sel:DWORD src1_sel:BYTE_0
	v_add_u32_sdwa v3, v3, sext(v4) dst_sel:DWORD dst_unused:UNUSED_PAD src0_sel:DWORD src1_sel:WORD_0
	v_lshlrev_b32_e32 v4, 1, v5
	v_lshrrev_b32_e32 v6, 2, v5
	v_and_b32_e32 v7, 3, v7
	s_movk_i32 s1, 0xffe0
	v_and_b32_e32 v4, 24, v4
	v_and_b32_e32 v6, 4, v6
	v_and_or_b32 v7, v5, s1, v7
	v_or3_b32 v4, v7, v6, v4
	s_cmp_lg_u32 s24, 3
	s_cbranch_scc1 .Lpa_skip0
	v_and_b32_e32 v9, 15, v5
	v_bfe_u32 v10, v5, 4, 2
	v_and_b32_e32 v5, 0xffffffc0, v5
	v_lshl_add_u32 v9, v9, 2, v10
	v_or_b32_e32 v5, v5, v9
.Lpa_skip0:
	v_mul_lo_u32 v5, v5, s42
	v_mul_lo_u32 v4, v4, s3
	v_add_u32_e32 v2, 0x2000, v2
	v_add_lshl_u32 v178, v3, v5, 1
	v_add_lshl_u32 v179, v4, v3, 1
	v_ashrrev_i32_e32 v3, 31, v2
	v_lshrrev_b32_e32 v3, 22, v3
	v_add_u32_e32 v3, v2, v3
	v_ashrrev_i32_e32 v3, 10, v3
	v_mul_i32_i24_e32 v4, 0x400, v3
	v_sub_u32_e32 v2, v2, v4
	v_lshrrev_b32_e32 v4, 4, v2
	v_bitop3_b32 v2, v4, v2, 32 bitop3:0x6c
	v_ashrrev_i32_e32 v5, 31, v2
	v_lshrrev_b32_e32 v5, 26, v5
	v_add_u32_e32 v5, v2, v5
	v_ashrrev_i32_e32 v6, 6, v5
	v_and_b32_e32 v5, 0xffc0, v5
	v_sub_u32_e32 v2, v2, v5
	v_lshrrev_b16_e32 v5, 7, v2
	v_lshlrev_b32_e32 v4, 3, v3
	v_and_b32_e32 v5, 1, v5
	v_and_b32_e32 v4, -16, v4
	v_lshlrev_b32_e32 v3, 5, v3
	v_add_u16_e32 v2, v2, v5
	v_add_u32_e32 v4, v6, v4
	v_and_b32_e32 v3, 32, v3
	v_ashrrev_i16_sdwa v2, v8, sext(v2) dst_sel:DWORD dst_unused:UNUSED_PAD src0_sel:DWORD src1_sel:BYTE_0
	v_add_u32_sdwa v2, v3, sext(v2) dst_sel:DWORD dst_unused:UNUSED_PAD src0_sel:DWORD src1_sel:WORD_0
	v_lshlrev_b32_e32 v3, 1, v4
	v_lshrrev_b32_e32 v5, 2, v4
	v_and_b32_e32 v6, 3, v6
	v_and_b32_e32 v3, 24, v3
	v_and_b32_e32 v5, 4, v5
	v_and_or_b32 v6, v4, s1, v6
	v_or3_b32 v3, v6, v5, v3
	s_cmp_lg_u32 s24, 3
	s_cbranch_scc1 .Lpa_skip1
	v_and_b32_e32 v9, 15, v4
	v_bfe_u32 v10, v4, 4, 2
	v_and_b32_e32 v4, 0xffffffc0, v4
	v_lshl_add_u32 v9, v9, 2, v10
	v_or_b32_e32 v4, v4, v9
.Lpa_skip1:
	v_mul_lo_u32 v4, v4, s42
	v_mul_lo_u32 v3, v3, s3
	v_add_lshl_u32 v180, v2, v4, 1
	v_add_lshl_u32 v181, v3, v2, 1
	v_cvt_f32_u32_e32 v2, s40
	s_abs_i32 s4, s73
	s_waitcnt lgkmcnt(0)
	s_and_b32 s17, s17, 0xffff
	s_and_b32 s21, s21, 0xffff
	v_rcp_iflag_f32_e32 v2, v2
	s_lshl_b32 s61, s42, 8
	s_lshl_b32 s62, s3, 8
	s_lshl_b32 s63, s42, 9
	v_mul_f32_e32 v2, 0x4f7ffffe, v2
	v_cvt_u32_f32_e32 v2, v2
	s_lshl_b32 s64, s3, 9
	s_ashr_i32 s1, s73, 31
	v_readlane_b32 s44, v255, 46
	v_readfirstlane_b32 s65, v2
	s_mul_i32 s5, s5, s65
	s_mul_hi_u32 s5, s65, s5
	s_add_i32 s65, s65, s5
	s_mul_hi_u32 s5, s4, s65
	s_mul_i32 s6, s5, s40
	s_sub_i32 s4, s4, s6
	s_add_i32 s6, s5, 1
	s_sub_i32 s7, s4, s40
	s_cmp_ge_u32 s4, s40
	s_cselect_b32 s5, s6, s5
	s_cselect_b32 s4, s7, s4
	s_add_i32 s6, s5, 1
	s_cmp_ge_u32 s4, s40
	s_cselect_b32 s4, s6, s5
	s_xor_b32 s4, s4, s1
	s_sub_i32 s1, s4, s1
	s_mul_i32 s1, s44, s1
	s_mul_i32 s4, s72, s64
	s_mov_b32 m0, s98
	s_mov_b32 s22, s18
	s_mov_b32 s23, s19
	s_add_i32 s10, s1, s4
	buffer_load_dwordx4 v179, s[20:23], s10 offen lds
	s_mov_b32 m0, s99
	s_mul_i32 s11, s73, s63
	buffer_load_dwordx4 v181, s[20:23], s10 offen lds
	s_mov_b32 m0, s48
	s_add_i32 s1, s10, s62
	buffer_load_dwordx4 v178, s[16:19], s11 offen lds
	s_mov_b32 m0, s97
	s_add_i32 s4, s11, s61
	buffer_load_dwordx4 v180, s[16:19], s11 offen lds
	s_mov_b32 m0, s93
	s_nop 0
	buffer_load_dwordx4 v179, s[20:23], s1 offen lds
	s_mov_b32 m0, s94
	s_nop 0
	buffer_load_dwordx4 v181, s[20:23], s1 offen lds
	s_mov_b32 m0, s95
	s_nop 0
	buffer_load_dwordx4 v178, s[16:19], s4 offen lds
	s_mov_b32 m0, s27
	s_nop 0
	buffer_load_dwordx4 v180, s[16:19], s4 offen lds
	v_readlane_b32 s4, v255, 9
	v_readlane_b32 s5, v255, 10
	s_andn2_b64 vcc, exec, s[4:5]
	s_cbranch_vccnz .LBB0_325
	s_barrier

; #define LAS __attribute__((address_space(3)))
; #define EPI_LANE() const int lane2 = fresh_lane(), fr = lane2 & 15, fq = lane2 >> 4
;     __device__ __forceinline__ void operator()(const f32x4 (&acc)[2][2][4][2], const Unit& u) const {
;     ...
;             EPI_LANE();
;             const float* cw = P->in[24] + (size_t)layer * 3 * F2; const float* cb = P->in[25] + (size_t)layer * F2;
;             bf16_t* eb = (bf16_t*)(P->ws + WS_EB);
;             const int ch0 = u.pn * 128 + wc * 32 + 8 * fq;
;             const float m0 = fr == 0 ? 1.f : 0.f, n0 = 1.f - m0, m15 = fr == 15 ? 1.f : 0.f, n15 = 1.f - m15;
;             LAS unsigned char* wl = lds + LDS_CW + wid * 1024;
;             { const int a_ = lane2 >> 3, q4 = (lane2 & 7) * 4;
;               const float* src = (a_ < 6 ? cw + (a_ >> 1) * F2 : cb) + (a_ & 1) * F + (unsigned)(u.pn * 128 + wc * 32 + q4);
;               const f32x4 wv = *(const f32x4*)src;
;               *(LAS f32x4*)(wl + lane2 * 16) = wv; }
;             asm volatile("s_waitcnt lgkmcnt(0)" ::: "memory");
; #pragma unroll
;             for (int ai = 0; ai < 2; ++ai) {
;                 const int rowb = u.pm * BM + ai * HALF + wr * 64, q = rowb >> 6;
;                 unsigned gq[4][4], pe[2][2][4];
; #pragma unroll
;                 for (int n = 0; n < 2; ++n) {
;                     f32x4 W[2][4];
; #pragma unroll
;                     for (int part = 0; part < 2; ++part)
; #pragma unroll
;                         for (int k = 0; k < 4; ++k) W[part][k] = *(const LAS f32x4*)(wl + (k * 2 + part) * 128 + (8 * fq + 4 * n) * 4);
; #pragma unroll
;                     for (int ep = 0; ep < 2; ++ep) {
;                         f32x2 cres[2][4];
; #pragma unroll
;                         for (int part = 0; part < 2; ++part) {
;                             const f32x2 w0 = (f32x2){W[part][0][2 * ep], W[part][0][2 * ep + 1]}, w1 = (f32x2){W[part][1][2 * ep], W[part][1][2 * ep + 1]};
;                             const f32x2 w2 = (f32x2){W[part][2][2 * ep], W[part][2][2 * ep + 1]}, bb = (f32x2){W[part][3][2 * ep], W[part][3][2 * ep + 1]};
;                             const f32x2 w0a = w0 * n0, w0b = w0 * m0, w2a = w2 * n15, w2b = w2 * m15;
;                             f32x2 X[4], R[4], L[4];
; #pragma unroll
;                             for (int m = 0; m < 4; ++m) { X[m] = (f32x2){acc[ai][part][m][n][2 * ep], acc[ai][part][m][n][2 * ep + 1]};
.LBB0_346:
	s_and_b64 vcc, exec, s[10:11]
	s_cbranch_vccz .LBB0_373
	s_cmp_eq_u32 s24, 3
	s_mov_b64 s[8:9], -1
	s_cbranch_scc0 .LBB0_373
	v_mbcnt_lo_u32_b32 v130, -1, 0
	v_mbcnt_hi_u32_b32 v130, -1, v130
	s_load_dwordx2 s[10:11], s[6:7], 0xe0
	v_readlane_b32 s3, v255, 12
	v_and_b32_e32 v131, 15, v130
	v_lshrrev_b32_e32 v129, 4, v130
	v_mov_b32_e32 v134, 0xbdd2d3e8
	v_mov_b32_e32 v135, 0xbdd2d3e8
	v_mov_b32_e32 v136, 0xc0135761
	v_mov_b32_e32 v137, 0xc0135761
	v_lshl_add_u32 v132, v129, 5, s3
	v_cmp_eq_u32_e64 s[6:7], 0, v131
	v_cmp_eq_u32_e64 s[8:9], 15, v131
	v_cmp_ne_u32_e64 s[56:57], 0, v131
	v_cmp_ne_u32_e64 s[58:59], 15, v131
	s_lshl_b32 s1, s72, 7
	s_or_b32 s1, s1, s49
	v_lshl_add_u32 v133, v129, 3, s1
	s_lshl_b32 s1, s73, 8
	s_add_i32 s1, s1, s33
	v_lshl_add_u32 v128, v131, 2, s1
	v_mul_lo_u32 v128, v128, s78
	v_lshl_add_u32 v128, v133, 1, v128
	s_lshl_b32 s1, s73, 2
	s_lshr_b32 s3, s33, 6
	s_add_i32 s1, s1, s3
	s_mul_i32 s1, s1, 0x2c0
	v_lshrrev_b32_e32 v129, 3, v133
	v_add_lshl_u32 v129, v129, s1, 6
	v_add_u32_e32 v162, 0x5800, v129
	s_waitcnt lgkmcnt(0)
	s_add_u32 s10, s10, 0x18660000
	s_addc_u32 s11, s11, 0
	ds_read_b64 v[202:203], v132 offset:0
	ds_read_b64 v[204:205], v132 offset:128
	ds_read_b64 v[206:207], v132 offset:256
	ds_read_b64 v[208:209], v132 offset:384
	ds_read_b64 v[210:211], v132 offset:512
	ds_read_b64 v[212:213], v132 offset:640
	ds_read_b64 v[214:215], v132 offset:768
	ds_read_b64 v[216:217], v132 offset:896
	s_waitcnt lgkmcnt(0)
	v_mov_b32_dpp v250, v52 row_shr:1 row_mask:0xf bank_mask:0xf bound_ctrl:1
	v_mov_b32_dpp v251, v53 row_shr:1 row_mask:0xf bank_mask:0xf bound_ctrl:1
	v_mov_b32_dpp v252, v116 row_shl:1 row_mask:0xf bank_mask:0xf bound_ctrl:1
	v_mov_b32_dpp v253, v117 row_shl:1 row_mask:0xf bank_mask:0xf bound_ctrl:1
	v_pk_fma_f32 v[234:235], v[116:117], v[206:207], v[214:215]
	v_pk_fma_f32 v[236:237], v[100:101], v[206:207], v[214:215]
	v_pk_fma_f32 v[238:239], v[84:85], v[206:207], v[214:215]
	v_pk_fma_f32 v[240:241], v[52:53], v[206:207], v[214:215]
	v_pk_fma_f32 v[234:235], v[250:251], v[202:203], v[234:235]
	v_pk_fma_f32 v[236:237], v[116:117], v[202:203], v[236:237]
	v_pk_fma_f32 v[238:239], v[100:101], v[202:203], v[238:239]
	v_pk_fma_f32 v[240:241], v[84:85], v[202:203], v[240:241]
	v_pk_fma_f32 v[234:235], v[100:101], v[210:211], v[234:235]
	v_pk_fma_f32 v[236:237], v[84:85], v[210:211], v[236:237]
	v_pk_fma_f32 v[238:239], v[52:53], v[210:211], v[238:239]
	v_pk_fma_f32 v[240:241], v[252:253], v[210:211], v[240:241]
	v_cvt_pk_bf16_f32 v184, v234, v235
	v_cvt_pk_bf16_f32 v192, v240, v241
	v_mov_b32_dpp v250, v68 row_shr:1 row_mask:0xf bank_mask:0xf bound_ctrl:1
	v_mov_b32_dpp v251, v69 row_shr:1 row_mask:0xf bank_mask:0xf bound_ctrl:1
	v_mov_b32_dpp v252, v124 row_shl:1 row_mask:0xf bank_mask:0xf bound_ctrl:1
	v_mov_b32_dpp v253, v125 row_shl:1 row_mask:0xf bank_mask:0xf bound_ctrl:1
	v_pk_fma_f32 v[242:243], v[124:125], v[208:209], v[216:217]
	v_pk_fma_f32 v[244:245], v[108:109], v[208:209], v[216:217]
	v_pk_fma_f32 v[246:247], v[92:93], v[208:209], v[216:217]
	v_pk_fma_f32 v[248:249], v[68:69], v[208:209], v[216:217]
	v_pk_fma_f32 v[242:243], v[250:251], v[204:205], v[242:243]
	v_pk_fma_f32 v[244:245], v[124:125], v[204:205], v[244:245]
	v_pk_fma_f32 v[246:247], v[108:109], v[204:205], v[246:247]
	v_pk_fma_f32 v[248:249], v[92:93], v[204:205], v[248:249]
	v_pk_fma_f32 v[242:243], v[108:109], v[212:213], v[242:243]
	v_pk_fma_f32 v[244:245], v[92:93], v[212:213], v[244:245]
	v_pk_fma_f32 v[246:247], v[68:69], v[212:213], v[246:247]
	v_pk_fma_f32 v[248:249], v[252:253], v[212:213], v[248:249]
	v_cvt_pk_bf16_f32 v188, v242, v243
	v_cvt_pk_bf16_f32 v154, v248, v249
	ds_read_b64 v[202:203], v132 offset:8
	ds_read_b64 v[204:205], v132 offset:136
	ds_read_b64 v[206:207], v132 offset:264
	ds_read_b64 v[208:209], v132 offset:392
	ds_read_b64 v[210:211], v132 offset:520
	ds_read_b64 v[212:213], v132 offset:648
	ds_read_b64 v[214:215], v132 offset:776
	ds_read_b64 v[216:217], v132 offset:904
	v_pk_mul_f32 v[138:139], v[234:235], v[234:235]
	v_pk_mul_f32 v[140:141], v[236:237], v[236:237]
	v_pk_mul_f32 v[142:143], v[238:239], v[238:239]
	v_pk_mul_f32 v[144:145], v[240:241], v[240:241]
	v_pk_fma_f32 v[138:139], v[138:139], v[134:135], v[136:137]
	v_pk_fma_f32 v[140:141], v[140:141], v[134:135], v[136:137]
	v_pk_fma_f32 v[142:143], v[142:143], v[134:135], v[136:137]
	v_pk_fma_f32 v[144:145], v[144:145], v[134:135], v[136:137]
	v_pk_mul_f32 v[138:139], v[234:235], v[138:139]
	v_pk_mul_f32 v[140:141], v[236:237], v[140:141]
	v_pk_mul_f32 v[142:143], v[238:239], v[142:143]
	v_pk_mul_f32 v[144:145], v[240:241], v[144:145]
	v_exp_f32_e32 v138, v138
	v_exp_f32_e32 v139, v139
	v_exp_f32_e32 v140, v140
	v_exp_f32_e32 v141, v141
	v_exp_f32_e32 v142, v142
	v_exp_f32_e32 v143, v143
	v_exp_f32_e32 v144, v144
	v_exp_f32_e32 v145, v145
	v_pk_mul_f32 v[146:147], v[234:235], v[242:243]
	v_pk_mul_f32 v[148:149], v[236:237], v[244:245]
	v_pk_mul_f32 v[150:151], v[238:239], v[246:247]
	v_pk_mul_f32 v[152:153], v[240:241], v[248:249]
	v_pk_add_f32 v[138:139], v[138:139], 1.0 op_sel_hi:[1,0]
	v_pk_add_f32 v[140:141], v[140:141], 1.0 op_sel_hi:[1,0]
	v_pk_add_f32 v[142:143], v[142:143], 1.0 op_sel_hi:[1,0]
	v_pk_add_f32 v[144:145], v[144:145], 1.0 op_sel_hi:[1,0]
	v_rcp_f32_e32 v138, v138
	v_rcp_f32_e32 v139, v139
	v_rcp_f32_e32 v140, v140
	v_rcp_f32_e32 v141, v141
	v_rcp_f32_e32 v142, v142
	v_rcp_f32_e32 v143, v143
	v_rcp_f32_e32 v144, v144
	v_rcp_f32_e32 v145, v145
	v_pk_mul_f32 v[146:147], v[146:147], v[138:139]
	v_pk_mul_f32 v[148:149], v[148:149], v[140:141]
	v_pk_mul_f32 v[150:151], v[150:151], v[142:143]
	v_pk_mul_f32 v[152:153], v[152:153], v[144:145]
	v_cvt_pk_bf16_f32 v218, v146, v147
	v_cvt_pk_bf16_f32 v222, v148, v149
	v_cvt_pk_bf16_f32 v226, v150, v151
	v_cvt_pk_bf16_f32 v230, v152, v153
	s_waitcnt lgkmcnt(0)
;     __device__ __forceinline__ void operator()(const f32x4 (&acc)[2][2][4][2], const Unit& u) const {
;     ...
;                     for (int ep = 0; ep < 2; ++ep) {
;                         f32x2 cres[2][4];
; #pragma unroll
;                         for (int part = 0; part < 2; ++part) {
;                             const f32x2 w0 = (f32x2){W[part][0][2 * ep], W[part][0][2 * ep + 1]}, w1 = (f32x2){W[part][1][2 * ep], W[part][1][2 * ep + 1]};
;                             const f32x2 w2 = (f32x2){W[part][2][2 * ep], W[part][2][2 * ep + 1]}, bb = (f32x2){W[part][3][2 * ep], W[part][3][2 * ep + 1]};
;                             const f32x2 w0a = w0 * n0, w0b = w0 * m0, w2a = w2 * n15, w2b = w2 * m15;
;                             f32x2 X[4], R[4], L[4];
; #pragma unroll
;                             for (int m = 0; m < 4; ++m) { X[m] = (f32x2){acc[ai][part][m][n][2 * ep], acc[ai][part][m][n][2 * ep + 1]};
;                                 R[m] = (f32x2){dpp_prev(X[m].x), dpp_prev(X[m].y)}; L[m] = (f32x2){dpp_next(X[m].x), dpp_next(X[m].y)}; }
; #pragma unroll
;                             for (int m = 0; m < 4; ++m) {
;                                 f32x2 c = X[m] * w1 + bb; c = R[m] * w0a + c; c = L[m] * w2a + c;
;                                 if (m > 0) c = R[m > 0 ? m - 1 : 0] * w0b + c;
;                                 if (m < 3) c = L[m < 3 ? m + 1 : 3] * w2b + c;
;                                 cres[part][m] = c;
;                             }
;                             pe[0][part][n * 2 + ep] = cvt_pk_bf16(cres[part][0].x, cres[part][0].y);
;                             pe[1][part][n * 2 + ep] = cvt_pk_bf16(cres[part][3].x, cres[part][3].y);
;                             __builtin_amdgcn_sched_barrier(0);
;                         }
; #pragma unroll
;                         for (int m = 0; m < 4; ++m) {
;                             const f32x2 a = cres[0][m], v = cres[1][m];
;                             const f32x2 t = (a * a) * (-0.10294324f) + (-2.3022082f), z = a * t;
;                             f32x2 d; d.x = __builtin_amdgcn_exp2f(z.x) + 1.f; d.y = __builtin_amdgcn_exp2f(z.y) + 1.f;
;                             f32x2 r; r.x = __builtin_amdgcn_rcpf(d.x); r.y = __builtin_amdgcn_rcpf(d.y);
;                             const f32x2 o = (a * v) * r;
;                             gq[m][n * 2 + ep] = cvt_pk_bf16(o.x, o.y);
	v_mov_b32_dpp v250, v54 row_shr:1 row_mask:0xf bank_mask:0xf bound_ctrl:1
	v_mov_b32_dpp v251, v55 row_shr:1 row_mask:0xf bank_mask:0xf bound_ctrl:1
	v_mov_b32_dpp v252, v118 row_shl:1 row_mask:0xf bank_mask:0xf bound_ctrl:1
	v_mov_b32_dpp v253, v119 row_shl:1 row_mask:0xf bank_mask:0xf bound_ctrl:1
	v_pk_fma_f32 v[234:235], v[118:119], v[206:207], v[214:215]
	v_pk_fma_f32 v[236:237], v[102:103], v[206:207], v[214:215]
	v_pk_fma_f32 v[238:239], v[86:87], v[206:207], v[214:215]
	v_pk_fma_f32 v[240:241], v[54:55], v[206:207], v[214:215]
	v_pk_fma_f32 v[234:235], v[250:251], v[202:203], v[234:235]
	v_pk_fma_f32 v[236:237], v[118:119], v[202:203], v[236:237]
	v_pk_fma_f32 v[238:239], v[102:103], v[202:203], v[238:239]
	v_pk_fma_f32 v[240:241], v[86:87], v[202:203], v[240:241]
	v_pk_fma_f32 v[234:235], v[102:103], v[210:211], v[234:235]
	v_pk_fma_f32 v[236:237], v[86:87], v[210:211], v[236:237]
	v_pk_fma_f32 v[238:239], v[54:55], v[210:211], v[238:239]
	v_pk_fma_f32 v[240:241], v[252:253], v[210:211], v[240:241]
	v_cvt_pk_bf16_f32 v185, v234, v235
	v_cvt_pk_bf16_f32 v193, v240, v241
	v_mov_b32_dpp v250, v70 row_shr:1 row_mask:0xf bank_mask:0xf bound_ctrl:1
	v_mov_b32_dpp v251, v71 row_shr:1 row_mask:0xf bank_mask:0xf bound_ctrl:1
	v_mov_b32_dpp v252, v126 row_shl:1 row_mask:0xf bank_mask:0xf bound_ctrl:1
	v_mov_b32_dpp v253, v127 row_shl:1 row_mask:0xf bank_mask:0xf bound_ctrl:1
	v_pk_fma_f32 v[242:243], v[126:127], v[208:209], v[216:217]
	v_pk_fma_f32 v[244:245], v[110:111], v[208:209], v[216:217]
	v_pk_fma_f32 v[246:247], v[94:95], v[208:209], v[216:217]
	v_pk_fma_f32 v[248:249], v[70:71], v[208:209], v[216:217]
	v_pk_fma_f32 v[242:243], v[250:251], v[204:205], v[242:243]
	v_pk_fma_f32 v[244:245], v[126:127], v[204:205], v[244:245]
	v_pk_fma_f32 v[246:247], v[110:111], v[204:205], v[246:247]
	v_pk_fma_f32 v[248:249], v[94:95], v[204:205], v[248:249]
	v_pk_fma_f32 v[242:243], v[110:111], v[212:213], v[242:243]
	v_pk_fma_f32 v[244:245], v[94:95], v[212:213], v[244:245]
	v_pk_fma_f32 v[246:247], v[70:71], v[212:213], v[246:247]
	v_pk_fma_f32 v[248:249], v[252:253], v[212:213], v[248:249]
	v_cvt_pk_bf16_f32 v189, v242, v243
	v_cvt_pk_bf16_f32 v155, v248, v249
	ds_read_b64 v[202:203], v132 offset:16
	ds_read_b64 v[204:205], v132 offset:144
	ds_read_b64 v[206:207], v132 offset:272
	ds_read_b64 v[208:209], v132 offset:400
	ds_read_b64 v[210:211], v132 offset:528
	ds_read_b64 v[212:213], v132 offset:656
	ds_read_b64 v[214:215], v132 offset:784
	ds_read_b64 v[216:217], v132 offset:912
	v_pk_mul_f32 v[138:139], v[234:235], v[234:235]
	v_pk_mul_f32 v[140:141], v[236:237], v[236:237]
	v_pk_mul_f32 v[142:143], v[238:239], v[238:239]
	v_pk_mul_f32 v[144:145], v[240:241], v[240:241]
	v_pk_fma_f32 v[138:139], v[138:139], v[134:135], v[136:137]
	v_pk_fma_f32 v[140:141], v[140:141], v[134:135], v[136:137]
	v_pk_fma_f32 v[142:143], v[142:143], v[134:135], v[136:137]
	v_pk_fma_f32 v[144:145], v[144:145], v[134:135], v[136:137]
	v_pk_mul_f32 v[138:139], v[234:235], v[138:139]
	v_pk_mul_f32 v[140:141], v[236:237], v[140:141]
	v_pk_mul_f32 v[142:143], v[238:239], v[142:143]
	v_pk_mul_f32 v[144:145], v[240:241], v[144:145]
	v_exp_f32_e32 v138, v138
	v_exp_f32_e32 v139, v139
	v_exp_f32_e32 v140, v140
	v_exp_f32_e32 v141, v141
	v_exp_f32_e32 v142, v142
	v_exp_f32_e32 v143, v143
	v_exp_f32_e32 v144, v144
	v_exp_f32_e32 v145, v145
	v_pk_mul_f32 v[146:147], v[234:235], v[242:243]
	v_pk_mul_f32 v[148:149], v[236:237], v[244:245]
	v_pk_mul_f32 v[150:151], v[238:239], v[246:247]
	v_pk_mul_f32 v[152:153], v[240:241], v[248:249]
	v_pk_add_f32 v[138:139], v[138:139], 1.0 op_sel_hi:[1,0]
	v_pk_add_f32 v[140:141], v[140:141], 1.0 op_sel_hi:[1,0]
	v_pk_add_f32 v[142:143], v[142:143], 1.0 op_sel_hi:[1,0]
	v_pk_add_f32 v[144:145], v[144:145], 1.0 op_sel_hi:[1,0]
	v_rcp_f32_e32 v138, v138
	v_rcp_f32_e32 v139, v139
	v_rcp_f32_e32 v140, v140
	v_rcp_f32_e32 v141, v141
	v_rcp_f32_e32 v142, v142
	v_rcp_f32_e32 v143, v143
	v_rcp_f32_e32 v144, v144
	v_rcp_f32_e32 v145, v145
	v_pk_mul_f32 v[146:147], v[146:147], v[138:139]
	v_pk_mul_f32 v[148:149], v[148:149], v[140:141]
	v_pk_mul_f32 v[150:151], v[150:151], v[142:143]
	v_pk_mul_f32 v[152:153], v[152:153], v[144:145]
	v_cvt_pk_bf16_f32 v219, v146, v147
	v_cvt_pk_bf16_f32 v223, v148, v149
	v_cvt_pk_bf16_f32 v227, v150, v151
	v_cvt_pk_bf16_f32 v231, v152, v153
	s_waitcnt lgkmcnt(0)
;     __device__ __forceinline__ void operator()(const f32x4 (&acc)[2][2][4][2], const Unit& u) const {
;     ...
;                     for (int ep = 0; ep < 2; ++ep) {
;                         f32x2 cres[2][4];
; #pragma unroll
;                         for (int part = 0; part < 2; ++part) {
;                             const f32x2 w0 = (f32x2){W[part][0][2 * ep], W[part][0][2 * ep + 1]}, w1 = (f32x2){W[part][1][2 * ep], W[part][1][2 * ep + 1]};
;                             const f32x2 w2 = (f32x2){W[part][2][2 * ep], W[part][2][2 * ep + 1]}, bb = (f32x2){W[part][3][2 * ep], W[part][3][2 * ep + 1]};
;                             const f32x2 w0a = w0 * n0, w0b = w0 * m0, w2a = w2 * n15, w2b = w2 * m15;
;                             f32x2 X[4], R[4], L[4];
; #pragma unroll
;                             for (int m = 0; m < 4; ++m) { X[m] = (f32x2){acc[ai][part][m][n][2 * ep], acc[ai][part][m][n][2 * ep + 1]};
;                                 R[m] = (f32x2){dpp_prev(X[m].x), dpp_prev(X[m].y)}; L[m] = (f32x2){dpp_next(X[m].x), dpp_next(X[m].y)}; }
; #pragma unroll
;                             for (int m = 0; m < 4; ++m) {
;                                 f32x2 c = X[m] * w1 + bb; c = R[m] * w0a + c; c = L[m] * w2a + c;
;                                 if (m > 0) c = R[m > 0 ? m - 1 : 0] * w0b + c;
;                                 if (m < 3) c = L[m < 3 ? m + 1 : 3] * w2b + c;
;                                 cres[part][m] = c;
;                             }
;                             pe[0][part][n * 2 + ep] = cvt_pk_bf16(cres[part][0].x, cres[part][0].y);
;                             pe[1][part][n * 2 + ep] = cvt_pk_bf16(cres[part][3].x, cres[part][3].y);
;                             __builtin_amdgcn_sched_barrier(0);
;                         }
; #pragma unroll
;                         for (int m = 0; m < 4; ++m) {
;                             const f32x2 a = cres[0][m], v = cres[1][m];
;                             const f32x2 t = (a * a) * (-0.10294324f) + (-2.3022082f), z = a * t;
;                             f32x2 d; d.x = __builtin_amdgcn_exp2f(z.x) + 1.f; d.y = __builtin_amdgcn_exp2f(z.y) + 1.f;
;                             f32x2 r; r.x = __builtin_amdgcn_rcpf(d.x); r.y = __builtin_amdgcn_rcpf(d.y);
;                             const f32x2 o = (a * v) * r;
;                             gq[m][n * 2 + ep] = cvt_pk_bf16(o.x, o.y);
	v_mov_b32_dpp v250, v48 row_shr:1 row_mask:0xf bank_mask:0xf bound_ctrl:1
	v_mov_b32_dpp v251, v49 row_shr:1 row_mask:0xf bank_mask:0xf bound_ctrl:1
	v_mov_b32_dpp v252, v112 row_shl:1 row_mask:0xf bank_mask:0xf bound_ctrl:1
	v_mov_b32_dpp v253, v113 row_shl:1 row_mask:0xf bank_mask:0xf bound_ctrl:1
	v_pk_fma_f32 v[234:235], v[112:113], v[206:207], v[214:215]
	v_pk_fma_f32 v[236:237], v[96:97], v[206:207], v[214:215]
	v_pk_fma_f32 v[238:239], v[80:81], v[206:207], v[214:215]
	v_pk_fma_f32 v[240:241], v[48:49], v[206:207], v[214:215]
	v_pk_fma_f32 v[234:235], v[250:251], v[202:203], v[234:235]
	v_pk_fma_f32 v[236:237], v[112:113], v[202:203], v[236:237]
	v_pk_fma_f32 v[238:239], v[96:97], v[202:203], v[238:239]
	v_pk_fma_f32 v[240:241], v[80:81], v[202:203], v[240:241]
	v_pk_fma_f32 v[234:235], v[96:97], v[210:211], v[234:235]
	v_pk_fma_f32 v[236:237], v[80:81], v[210:211], v[236:237]
	v_pk_fma_f32 v[238:239], v[48:49], v[210:211], v[238:239]
	v_pk_fma_f32 v[240:241], v[252:253], v[210:211], v[240:241]
	v_cvt_pk_bf16_f32 v186, v234, v235
	v_cvt_pk_bf16_f32 v194, v240, v241
	v_mov_b32_dpp v250, v60 row_shr:1 row_mask:0xf bank_mask:0xf bound_ctrl:1
	v_mov_b32_dpp v251, v61 row_shr:1 row_mask:0xf bank_mask:0xf bound_ctrl:1
	v_mov_b32_dpp v252, v120 row_shl:1 row_mask:0xf bank_mask:0xf bound_ctrl:1
	v_mov_b32_dpp v253, v121 row_shl:1 row_mask:0xf bank_mask:0xf bound_ctrl:1
	v_pk_fma_f32 v[242:243], v[120:121], v[208:209], v[216:217]
	v_pk_fma_f32 v[244:245], v[104:105], v[208:209], v[216:217]
	v_pk_fma_f32 v[246:247], v[88:89], v[208:209], v[216:217]
	v_pk_fma_f32 v[248:249], v[60:61], v[208:209], v[216:217]
	v_pk_fma_f32 v[242:243], v[250:251], v[204:205], v[242:243]
	v_pk_fma_f32 v[244:245], v[120:121], v[204:205], v[244:245]
	v_pk_fma_f32 v[246:247], v[104:105], v[204:205], v[246:247]
	v_pk_fma_f32 v[248:249], v[88:89], v[204:205], v[248:249]
	v_pk_fma_f32 v[242:243], v[104:105], v[212:213], v[242:243]
	v_pk_fma_f32 v[244:245], v[88:89], v[212:213], v[244:245]
	v_pk_fma_f32 v[246:247], v[60:61], v[212:213], v[246:247]
	v_pk_fma_f32 v[248:249], v[252:253], v[212:213], v[248:249]
	v_cvt_pk_bf16_f32 v190, v242, v243
	v_cvt_pk_bf16_f32 v156, v248, v249
	ds_read_b64 v[202:203], v132 offset:24
	ds_read_b64 v[204:205], v132 offset:152
	ds_read_b64 v[206:207], v132 offset:280
	ds_read_b64 v[208:209], v132 offset:408
	ds_read_b64 v[210:211], v132 offset:536
	ds_read_b64 v[212:213], v132 offset:664
	ds_read_b64 v[214:215], v132 offset:792
	ds_read_b64 v[216:217], v132 offset:920
	v_pk_mul_f32 v[138:139], v[234:235], v[234:235]
	v_pk_mul_f32 v[140:141], v[236:237], v[236:237]
	v_pk_mul_f32 v[142:143], v[238:239], v[238:239]
	v_pk_mul_f32 v[144:145], v[240:241], v[240:241]
	v_pk_fma_f32 v[138:139], v[138:139], v[134:135], v[136:137]
	v_pk_fma_f32 v[140:141], v[140:141], v[134:135], v[136:137]
	v_pk_fma_f32 v[142:143], v[142:143], v[134:135], v[136:137]
	v_pk_fma_f32 v[144:145], v[144:145], v[134:135], v[136:137]
	v_pk_mul_f32 v[138:139], v[234:235], v[138:139]
	v_pk_mul_f32 v[140:141], v[236:237], v[140:141]
	v_pk_mul_f32 v[142:143], v[238:239], v[142:143]
	v_pk_mul_f32 v[144:145], v[240:241], v[144:145]
	v_exp_f32_e32 v138, v138
	v_exp_f32_e32 v139, v139
	v_exp_f32_e32 v140, v140
	v_exp_f32_e32 v141, v141
	v_exp_f32_e32 v142, v142
	v_exp_f32_e32 v143, v143
	v_exp_f32_e32 v144, v144
	v_exp_f32_e32 v145, v145
	v_pk_mul_f32 v[146:147], v[234:235], v[242:243]
	v_pk_mul_f32 v[148:149], v[236:237], v[244:245]
	v_pk_mul_f32 v[150:151], v[238:239], v[246:247]
	v_pk_mul_f32 v[152:153], v[240:241], v[248:249]
	v_pk_add_f32 v[138:139], v[138:139], 1.0 op_sel_hi:[1,0]
	v_pk_add_f32 v[140:141], v[140:141], 1.0 op_sel_hi:[1,0]
	v_pk_add_f32 v[142:143], v[142:143], 1.0 op_sel_hi:[1,0]
	v_pk_add_f32 v[144:145], v[144:145], 1.0 op_sel_hi:[1,0]
	v_rcp_f32_e32 v138, v138
	v_rcp_f32_e32 v139, v139
	v_rcp_f32_e32 v140, v140
	v_rcp_f32_e32 v141, v141
	v_rcp_f32_e32 v142, v142
	v_rcp_f32_e32 v143, v143
	v_rcp_f32_e32 v144, v144
	v_rcp_f32_e32 v145, v145
	v_pk_mul_f32 v[146:147], v[146:147], v[138:139]
	v_pk_mul_f32 v[148:149], v[148:149], v[140:141]
	v_pk_mul_f32 v[150:151], v[150:151], v[142:143]
	v_pk_mul_f32 v[152:153], v[152:153], v[144:145]
	v_cvt_pk_bf16_f32 v220, v146, v147
	v_cvt_pk_bf16_f32 v224, v148, v149
	v_cvt_pk_bf16_f32 v228, v150, v151
	v_cvt_pk_bf16_f32 v232, v152, v153
	s_waitcnt lgkmcnt(0)
;     __device__ __forceinline__ void operator()(const f32x4 (&acc)[2][2][4][2], const Unit& u) const {
;     ...
;                     for (int ep = 0; ep < 2; ++ep) {
;                         f32x2 cres[2][4];
; #pragma unroll
;                         for (int part = 0; part < 2; ++part) {
;                             const f32x2 w0 = (f32x2){W[part][0][2 * ep], W[part][0][2 * ep + 1]}, w1 = (f32x2){W[part][1][2 * ep], W[part][1][2 * ep + 1]};
;                             const f32x2 w2 = (f32x2){W[part][2][2 * ep], W[part][2][2 * ep + 1]}, bb = (f32x2){W[part][3][2 * ep], W[part][3][2 * ep + 1]};
;                             const f32x2 w0a = w0 * n0, w0b = w0 * m0, w2a = w2 * n15, w2b = w2 * m15;
;                             f32x2 X[4], R[4], L[4];
; #pragma unroll
;                             for (int m = 0; m < 4; ++m) { X[m] = (f32x2){acc[ai][part][m][n][2 * ep], acc[ai][part][m][n][2 * ep + 1]};
;                                 R[m] = (f32x2){dpp_prev(X[m].x), dpp_prev(X[m].y)}; L[m] = (f32x2){dpp_next(X[m].x), dpp_next(X[m].y)}; }
; #pragma unroll
;                             for (int m = 0; m < 4; ++m) {
;                                 f32x2 c = X[m] * w1 + bb; c = R[m] * w0a + c; c = L[m] * w2a + c;
;                                 if (m > 0) c = R[m > 0 ? m - 1 : 0] * w0b + c;
;                                 if (m < 3) c = L[m < 3 ? m + 1 : 3] * w2b + c;
;                                 cres[part][m] = c;
;                             }
;                             pe[0][part][n * 2 + ep] = cvt_pk_bf16(cres[part][0].x, cres[part][0].y);
;                             pe[1][part][n * 2 + ep] = cvt_pk_bf16(cres[part][3].x, cres[part][3].y);
;                             __builtin_amdgcn_sched_barrier(0);
;                         }
; #pragma unroll
;                         for (int m = 0; m < 4; ++m) {
;                             const f32x2 a = cres[0][m], v = cres[1][m];
;                             const f32x2 t = (a * a) * (-0.10294324f) + (-2.3022082f), z = a * t;
;                             f32x2 d; d.x = __builtin_amdgcn_exp2f(z.x) + 1.f; d.y = __builtin_amdgcn_exp2f(z.y) + 1.f;
;                             f32x2 r; r.x = __builtin_amdgcn_rcpf(d.x); r.y = __builtin_amdgcn_rcpf(d.y);
;                             const f32x2 o = (a * v) * r;
;                             gq[m][n * 2 + ep] = cvt_pk_bf16(o.x, o.y);
	v_mov_b32_dpp v250, v50 row_shr:1 row_mask:0xf bank_mask:0xf bound_ctrl:1
	v_mov_b32_dpp v251, v51 row_shr:1 row_mask:0xf bank_mask:0xf bound_ctrl:1
	v_mov_b32_dpp v252, v114 row_shl:1 row_mask:0xf bank_mask:0xf bound_ctrl:1
	v_mov_b32_dpp v253, v115 row_shl:1 row_mask:0xf bank_mask:0xf bound_ctrl:1
	v_pk_fma_f32 v[234:235], v[114:115], v[206:207], v[214:215]
	v_pk_fma_f32 v[236:237], v[98:99], v[206:207], v[214:215]
	v_pk_fma_f32 v[238:239], v[82:83], v[206:207], v[214:215]
	v_pk_fma_f32 v[240:241], v[50:51], v[206:207], v[214:215]
	v_pk_fma_f32 v[234:235], v[250:251], v[202:203], v[234:235]
	v_pk_fma_f32 v[236:237], v[114:115], v[202:203], v[236:237]
	v_pk_fma_f32 v[238:239], v[98:99], v[202:203], v[238:239]
	v_pk_fma_f32 v[240:241], v[82:83], v[202:203], v[240:241]
	v_pk_fma_f32 v[234:235], v[98:99], v[210:211], v[234:235]
	v_pk_fma_f32 v[236:237], v[82:83], v[210:211], v[236:237]
	v_pk_fma_f32 v[238:239], v[50:51], v[210:211], v[238:239]
	v_pk_fma_f32 v[240:241], v[252:253], v[210:211], v[240:241]
	v_cvt_pk_bf16_f32 v187, v234, v235
	v_cvt_pk_bf16_f32 v195, v240, v241
	v_mov_b32_dpp v250, v62 row_shr:1 row_mask:0xf bank_mask:0xf bound_ctrl:1
	v_mov_b32_dpp v251, v63 row_shr:1 row_mask:0xf bank_mask:0xf bound_ctrl:1
	v_mov_b32_dpp v252, v122 row_shl:1 row_mask:0xf bank_mask:0xf bound_ctrl:1
	v_mov_b32_dpp v253, v123 row_shl:1 row_mask:0xf bank_mask:0xf bound_ctrl:1
	v_pk_fma_f32 v[242:243], v[122:123], v[208:209], v[216:217]
	v_pk_fma_f32 v[244:245], v[106:107], v[208:209], v[216:217]
	v_pk_fma_f32 v[246:247], v[90:91], v[208:209], v[216:217]
	v_pk_fma_f32 v[248:249], v[62:63], v[208:209], v[216:217]
	v_pk_fma_f32 v[242:243], v[250:251], v[204:205], v[242:243]
	v_pk_fma_f32 v[244:245], v[122:123], v[204:205], v[244:245]
	v_pk_fma_f32 v[246:247], v[106:107], v[204:205], v[246:247]
	v_pk_fma_f32 v[248:249], v[90:91], v[204:205], v[248:249]
	v_pk_fma_f32 v[242:243], v[106:107], v[212:213], v[242:243]
	v_pk_fma_f32 v[244:245], v[90:91], v[212:213], v[244:245]
	v_pk_fma_f32 v[246:247], v[62:63], v[212:213], v[246:247]
	v_pk_fma_f32 v[248:249], v[252:253], v[212:213], v[248:249]
	v_cvt_pk_bf16_f32 v191, v242, v243
	v_cvt_pk_bf16_f32 v157, v248, v249
	ds_read_b64 v[202:203], v132 offset:0
	ds_read_b64 v[204:205], v132 offset:128
	ds_read_b64 v[206:207], v132 offset:256
	ds_read_b64 v[208:209], v132 offset:384
	ds_read_b64 v[210:211], v132 offset:512
	ds_read_b64 v[212:213], v132 offset:640
	ds_read_b64 v[214:215], v132 offset:768
	ds_read_b64 v[216:217], v132 offset:896
	v_pk_mul_f32 v[138:139], v[234:235], v[234:235]
	v_pk_mul_f32 v[140:141], v[236:237], v[236:237]
	v_pk_mul_f32 v[142:143], v[238:239], v[238:239]
	v_pk_mul_f32 v[144:145], v[240:241], v[240:241]
	v_pk_fma_f32 v[138:139], v[138:139], v[134:135], v[136:137]
	v_pk_fma_f32 v[140:141], v[140:141], v[134:135], v[136:137]
	v_pk_fma_f32 v[142:143], v[142:143], v[134:135], v[136:137]
	v_pk_fma_f32 v[144:145], v[144:145], v[134:135], v[136:137]
	v_pk_mul_f32 v[138:139], v[234:235], v[138:139]
	v_pk_mul_f32 v[140:141], v[236:237], v[140:141]
	v_pk_mul_f32 v[142:143], v[238:239], v[142:143]
	v_pk_mul_f32 v[144:145], v[240:241], v[144:145]
	v_exp_f32_e32 v138, v138
	v_exp_f32_e32 v139, v139
	v_exp_f32_e32 v140, v140
	v_exp_f32_e32 v141, v141
	v_exp_f32_e32 v142, v142
	v_exp_f32_e32 v143, v143
	v_exp_f32_e32 v144, v144
	v_exp_f32_e32 v145, v145
	v_pk_mul_f32 v[146:147], v[234:235], v[242:243]
	v_pk_mul_f32 v[148:149], v[236:237], v[244:245]
	v_pk_mul_f32 v[150:151], v[238:239], v[246:247]
	v_pk_mul_f32 v[152:153], v[240:241], v[248:249]
	v_pk_add_f32 v[138:139], v[138:139], 1.0 op_sel_hi:[1,0]
	v_pk_add_f32 v[140:141], v[140:141], 1.0 op_sel_hi:[1,0]
	v_pk_add_f32 v[142:143], v[142:143], 1.0 op_sel_hi:[1,0]
	v_pk_add_f32 v[144:145], v[144:145], 1.0 op_sel_hi:[1,0]
	v_rcp_f32_e32 v138, v138
	v_rcp_f32_e32 v139, v139
	v_rcp_f32_e32 v140, v140
	v_rcp_f32_e32 v141, v141
	v_rcp_f32_e32 v142, v142
	v_rcp_f32_e32 v143, v143
	v_rcp_f32_e32 v144, v144
	v_rcp_f32_e32 v145, v145
	v_pk_mul_f32 v[146:147], v[146:147], v[138:139]
	v_pk_mul_f32 v[148:149], v[148:149], v[140:141]
	v_pk_mul_f32 v[150:151], v[150:151], v[142:143]
	v_pk_mul_f32 v[152:153], v[152:153], v[144:145]
	v_cvt_pk_bf16_f32 v221, v146, v147
	v_cvt_pk_bf16_f32 v225, v148, v149
	v_cvt_pk_bf16_f32 v229, v150, v151
	v_cvt_pk_bf16_f32 v233, v152, v153
	s_mov_b64 s[22:23], exec
	s_mov_b64 exec, s[6:7]
	v_cvt_pk_bf16_f32 v138, v116, v117
	v_cvt_pk_bf16_f32 v139, v118, v119
	v_cvt_pk_bf16_f32 v140, v112, v113
	v_cvt_pk_bf16_f32 v141, v114, v115
	v_cvt_pk_bf16_f32 v142, v124, v125
	v_cvt_pk_bf16_f32 v143, v126, v127
	v_cvt_pk_bf16_f32 v144, v120, v121
	v_cvt_pk_bf16_f32 v145, v122, v123
	global_store_dwordx4 v129, v[138:141], s[10:11]
	global_store_dwordx4 v129, v[142:145], s[10:11] offset:16
	global_store_dwordx4 v129, v[184:187], s[10:11] offset:32
	global_store_dwordx4 v129, v[188:191], s[10:11] offset:48
	s_mov_b64 exec, s[8:9]
	v_cvt_pk_bf16_f32 v146, v52, v53
	v_cvt_pk_bf16_f32 v147, v54, v55
	v_cvt_pk_bf16_f32 v148, v48, v49
	v_cvt_pk_bf16_f32 v149, v50, v51
	v_cvt_pk_bf16_f32 v150, v68, v69
	v_cvt_pk_bf16_f32 v151, v70, v71
	v_cvt_pk_bf16_f32 v152, v60, v61
	v_cvt_pk_bf16_f32 v153, v62, v63
	global_store_dwordx4 v162, v[146:149], s[10:11]
	global_store_dwordx4 v162, v[150:153], s[10:11] offset:16
	global_store_dwordx4 v162, v[192:195], s[10:11] offset:32
	global_store_dwordx4 v162, v[154:157], s[10:11] offset:48
	s_mov_b64 exec, s[56:57]
	global_store_dwordx4 v128, v[218:221], s[52:53]
	s_mov_b64 exec, s[22:23]
	v_add_u32_e32 v133, 0x1600, v128
	v_add_u32_e32 v130, 0x2c00, v128
	v_add_u32_e32 v131, 0x4200, v128
	global_store_dwordx4 v133, v[222:225], s[52:53]
	global_store_dwordx4 v130, v[226:229], s[52:53]
	s_mov_b64 exec, s[58:59]
	global_store_dwordx4 v131, v[230:233], s[52:53]
	s_mov_b64 exec, s[22:23]
	v_add_u32_e32 v128, 0xb0000, v128
	v_add_u32_e32 v129, 0x16000, v129
	v_add_u32_e32 v162, 0x16000, v162
	s_nop 1
	s_waitcnt lgkmcnt(0)
;     __device__ __forceinline__ void operator()(const f32x4 (&acc)[2][2][4][2], const Unit& u) const {
;     ...
;                     for (int ep = 0; ep < 2; ++ep) {
;                         f32x2 cres[2][4];
; #pragma unroll
;                         for (int part = 0; part < 2; ++part) {
;                             const f32x2 w0 = (f32x2){W[part][0][2 * ep], W[part][0][2 * ep + 1]}, w1 = (f32x2){W[part][1][2 * ep], W[part][1][2 * ep + 1]};
;                             const f32x2 w2 = (f32x2){W[part][2][2 * ep], W[part][2][2 * ep + 1]}, bb = (f32x2){W[part][3][2 * ep], W[part][3][2 * ep + 1]};
;                             const f32x2 w0a = w0 * n0, w0b = w0 * m0, w2a = w2 * n15, w2b = w2 * m15;
;                             f32x2 X[4], R[4], L[4];
; #pragma unroll
;                             for (int m = 0; m < 4; ++m) { X[m] = (f32x2){acc[ai][part][m][n][2 * ep], acc[ai][part][m][n][2 * ep + 1]};
;                                 R[m] = (f32x2){dpp_prev(X[m].x), dpp_prev(X[m].y)}; L[m] = (f32x2){dpp_next(X[m].x), dpp_next(X[m].y)}; }
; #pragma unroll
;                             for (int m = 0; m < 4; ++m) {
;                                 f32x2 c = X[m] * w1 + bb; c = R[m] * w0a + c; c = L[m] * w2a + c;
;                                 if (m > 0) c = R[m > 0 ? m - 1 : 0] * w0b + c;
;                                 if (m < 3) c = L[m < 3 ? m + 1 : 3] * w2b + c;
;                                 cres[part][m] = c;
;                             }
;                             pe[0][part][n * 2 + ep] = cvt_pk_bf16(cres[part][0].x, cres[part][0].y);
;                             pe[1][part][n * 2 + ep] = cvt_pk_bf16(cres[part][3].x, cres[part][3].y);
;                             __builtin_amdgcn_sched_barrier(0);
;                         }
; #pragma unroll
;                         for (int m = 0; m < 4; ++m) {
;                             const f32x2 a = cres[0][m], v = cres[1][m];
;                             const f32x2 t = (a * a) * (-0.10294324f) + (-2.3022082f), z = a * t;
;                             f32x2 d; d.x = __builtin_amdgcn_exp2f(z.x) + 1.f; d.y = __builtin_amdgcn_exp2f(z.y) + 1.f;
;                             f32x2 r; r.x = __builtin_amdgcn_rcpf(d.x); r.y = __builtin_amdgcn_rcpf(d.y);
;                             const f32x2 o = (a * v) * r;
;                             gq[m][n * 2 + ep] = cvt_pk_bf16(o.x, o.y);
	v_mov_b32_dpp v250, v4 row_shr:1 row_mask:0xf bank_mask:0xf bound_ctrl:1
	v_mov_b32_dpp v251, v5 row_shr:1 row_mask:0xf bank_mask:0xf bound_ctrl:1
	v_mov_b32_dpp v252, v64 row_shl:1 row_mask:0xf bank_mask:0xf bound_ctrl:1
	v_mov_b32_dpp v253, v65 row_shl:1 row_mask:0xf bank_mask:0xf bound_ctrl:1
	v_pk_fma_f32 v[234:235], v[64:65], v[206:207], v[214:215]
	v_pk_fma_f32 v[236:237], v[36:37], v[206:207], v[214:215]
	v_pk_fma_f32 v[238:239], v[20:21], v[206:207], v[214:215]
	v_pk_fma_f32 v[240:241], v[4:5], v[206:207], v[214:215]
	v_pk_fma_f32 v[234:235], v[250:251], v[202:203], v[234:235]
	v_pk_fma_f32 v[236:237], v[64:65], v[202:203], v[236:237]
	v_pk_fma_f32 v[238:239], v[36:37], v[202:203], v[238:239]
	v_pk_fma_f32 v[240:241], v[20:21], v[202:203], v[240:241]
	v_pk_fma_f32 v[234:235], v[36:37], v[210:211], v[234:235]
	v_pk_fma_f32 v[236:237], v[20:21], v[210:211], v[236:237]
	v_pk_fma_f32 v[238:239], v[4:5], v[210:211], v[238:239]
	v_pk_fma_f32 v[240:241], v[252:253], v[210:211], v[240:241]
	v_cvt_pk_bf16_f32 v184, v234, v235
	v_cvt_pk_bf16_f32 v192, v240, v241
	v_mov_b32_dpp v250, v12 row_shr:1 row_mask:0xf bank_mask:0xf bound_ctrl:1
	v_mov_b32_dpp v251, v13 row_shr:1 row_mask:0xf bank_mask:0xf bound_ctrl:1
	v_mov_b32_dpp v252, v76 row_shl:1 row_mask:0xf bank_mask:0xf bound_ctrl:1
	v_mov_b32_dpp v253, v77 row_shl:1 row_mask:0xf bank_mask:0xf bound_ctrl:1
	v_pk_fma_f32 v[242:243], v[76:77], v[208:209], v[216:217]
	v_pk_fma_f32 v[244:245], v[44:45], v[208:209], v[216:217]
	v_pk_fma_f32 v[246:247], v[28:29], v[208:209], v[216:217]
	v_pk_fma_f32 v[248:249], v[12:13], v[208:209], v[216:217]
	v_pk_fma_f32 v[242:243], v[250:251], v[204:205], v[242:243]
	v_pk_fma_f32 v[244:245], v[76:77], v[204:205], v[244:245]
	v_pk_fma_f32 v[246:247], v[44:45], v[204:205], v[246:247]
	v_pk_fma_f32 v[248:249], v[28:29], v[204:205], v[248:249]
	v_pk_fma_f32 v[242:243], v[44:45], v[212:213], v[242:243]
	v_pk_fma_f32 v[244:245], v[28:29], v[212:213], v[244:245]
	v_pk_fma_f32 v[246:247], v[12:13], v[212:213], v[246:247]
	v_pk_fma_f32 v[248:249], v[252:253], v[212:213], v[248:249]
	v_cvt_pk_bf16_f32 v188, v242, v243
	v_cvt_pk_bf16_f32 v154, v248, v249
	ds_read_b64 v[202:203], v132 offset:8
	ds_read_b64 v[204:205], v132 offset:136
	ds_read_b64 v[206:207], v132 offset:264
	ds_read_b64 v[208:209], v132 offset:392
	ds_read_b64 v[210:211], v132 offset:520
	ds_read_b64 v[212:213], v132 offset:648
	ds_read_b64 v[214:215], v132 offset:776
	ds_read_b64 v[216:217], v132 offset:904
	v_pk_mul_f32 v[138:139], v[234:235], v[234:235]
	v_pk_mul_f32 v[140:141], v[236:237], v[236:237]
	v_pk_mul_f32 v[142:143], v[238:239], v[238:239]
	v_pk_mul_f32 v[144:145], v[240:241], v[240:241]
	v_pk_fma_f32 v[138:139], v[138:139], v[134:135], v[136:137]
	v_pk_fma_f32 v[140:141], v[140:141], v[134:135], v[136:137]
	v_pk_fma_f32 v[142:143], v[142:143], v[134:135], v[136:137]
	v_pk_fma_f32 v[144:145], v[144:145], v[134:135], v[136:137]
	v_pk_mul_f32 v[138:139], v[234:235], v[138:139]
	v_pk_mul_f32 v[140:141], v[236:237], v[140:141]
	v_pk_mul_f32 v[142:143], v[238:239], v[142:143]
	v_pk_mul_f32 v[144:145], v[240:241], v[144:145]
	v_exp_f32_e32 v138, v138
	v_exp_f32_e32 v139, v139
	v_exp_f32_e32 v140, v140
	v_exp_f32_e32 v141, v141
	v_exp_f32_e32 v142, v142
	v_exp_f32_e32 v143, v143
	v_exp_f32_e32 v144, v144
	v_exp_f32_e32 v145, v145
	v_pk_mul_f32 v[146:147], v[234:235], v[242:243]
	v_pk_mul_f32 v[148:149], v[236:237], v[244:245]
	v_pk_mul_f32 v[150:151], v[238:239], v[246:247]
	v_pk_mul_f32 v[152:153], v[240:241], v[248:249]
	v_pk_add_f32 v[138:139], v[138:139], 1.0 op_sel_hi:[1,0]
	v_pk_add_f32 v[140:141], v[140:141], 1.0 op_sel_hi:[1,0]
	v_pk_add_f32 v[142:143], v[142:143], 1.0 op_sel_hi:[1,0]
	v_pk_add_f32 v[144:145], v[144:145], 1.0 op_sel_hi:[1,0]
	v_rcp_f32_e32 v138, v138
	v_rcp_f32_e32 v139, v139
	v_rcp_f32_e32 v140, v140
	v_rcp_f32_e32 v141, v141
	v_rcp_f32_e32 v142, v142
	v_rcp_f32_e32 v143, v143
	v_rcp_f32_e32 v144, v144
	v_rcp_f32_e32 v145, v145
	v_pk_mul_f32 v[146:147], v[146:147], v[138:139]
	v_pk_mul_f32 v[148:149], v[148:149], v[140:141]
	v_pk_mul_f32 v[150:151], v[150:151], v[142:143]
	v_pk_mul_f32 v[152:153], v[152:153], v[144:145]
	v_cvt_pk_bf16_f32 v218, v146, v147
	v_cvt_pk_bf16_f32 v222, v148, v149
	v_cvt_pk_bf16_f32 v226, v150, v151
	v_cvt_pk_bf16_f32 v230, v152, v153
	s_waitcnt lgkmcnt(0)
;     __device__ __forceinline__ void operator()(const f32x4 (&acc)[2][2][4][2], const Unit& u) const {
;     ...
;                     for (int ep = 0; ep < 2; ++ep) {
;                         f32x2 cres[2][4];
; #pragma unroll
;                         for (int part = 0; part < 2; ++part) {
;                             const f32x2 w0 = (f32x2){W[part][0][2 * ep], W[part][0][2 * ep + 1]}, w1 = (f32x2){W[part][1][2 * ep], W[part][1][2 * ep + 1]};
;                             const f32x2 w2 = (f32x2){W[part][2][2 * ep], W[part][2][2 * ep + 1]}, bb = (f32x2){W[part][3][2 * ep], W[part][3][2 * ep + 1]};
;                             const f32x2 w0a = w0 * n0, w0b = w0 * m0, w2a = w2 * n15, w2b = w2 * m15;
;                             f32x2 X[4], R[4], L[4];
; #pragma unroll
;                             for (int m = 0; m < 4; ++m) { X[m] = (f32x2){acc[ai][part][m][n][2 * ep], acc[ai][part][m][n][2 * ep + 1]};
;                                 R[m] = (f32x2){dpp_prev(X[m].x), dpp_prev(X[m].y)}; L[m] = (f32x2){dpp_next(X[m].x), dpp_next(X[m].y)}; }
; #pragma unroll
;                             for (int m = 0; m < 4; ++m) {
;                                 f32x2 c = X[m] * w1 + bb; c = R[m] * w0a + c; c = L[m] * w2a + c;
;                                 if (m > 0) c = R[m > 0 ? m - 1 : 0] * w0b + c;
;                                 if (m < 3) c = L[m < 3 ? m + 1 : 3] * w2b + c;
;                                 cres[part][m] = c;
;                             }
;                             pe[0][part][n * 2 + ep] = cvt_pk_bf16(cres[part][0].x, cres[part][0].y);
;                             pe[1][part][n * 2 + ep] = cvt_pk_bf16(cres[part][3].x, cres[part][3].y);
;                             __builtin_amdgcn_sched_barrier(0);
;                         }
; #pragma unroll
;                         for (int m = 0; m < 4; ++m) {
;                             const f32x2 a = cres[0][m], v = cres[1][m];
;                             const f32x2 t = (a * a) * (-0.10294324f) + (-2.3022082f), z = a * t;
;                             f32x2 d; d.x = __builtin_amdgcn_exp2f(z.x) + 1.f; d.y = __builtin_amdgcn_exp2f(z.y) + 1.f;
;                             f32x2 r; r.x = __builtin_amdgcn_rcpf(d.x); r.y = __builtin_amdgcn_rcpf(d.y);
;                             const f32x2 o = (a * v) * r;
;                             gq[m][n * 2 + ep] = cvt_pk_bf16(o.x, o.y);
	v_mov_b32_dpp v250, v6 row_shr:1 row_mask:0xf bank_mask:0xf bound_ctrl:1
	v_mov_b32_dpp v251, v7 row_shr:1 row_mask:0xf bank_mask:0xf bound_ctrl:1
	v_mov_b32_dpp v252, v66 row_shl:1 row_mask:0xf bank_mask:0xf bound_ctrl:1
	v_mov_b32_dpp v253, v67 row_shl:1 row_mask:0xf bank_mask:0xf bound_ctrl:1
	v_pk_fma_f32 v[234:235], v[66:67], v[206:207], v[214:215]
	v_pk_fma_f32 v[236:237], v[38:39], v[206:207], v[214:215]
	v_pk_fma_f32 v[238:239], v[22:23], v[206:207], v[214:215]
	v_pk_fma_f32 v[240:241], v[6:7], v[206:207], v[214:215]
	v_pk_fma_f32 v[234:235], v[250:251], v[202:203], v[234:235]
	v_pk_fma_f32 v[236:237], v[66:67], v[202:203], v[236:237]
	v_pk_fma_f32 v[238:239], v[38:39], v[202:203], v[238:239]
	v_pk_fma_f32 v[240:241], v[22:23], v[202:203], v[240:241]
	v_pk_fma_f32 v[234:235], v[38:39], v[210:211], v[234:235]
	v_pk_fma_f32 v[236:237], v[22:23], v[210:211], v[236:237]
	v_pk_fma_f32 v[238:239], v[6:7], v[210:211], v[238:239]
	v_pk_fma_f32 v[240:241], v[252:253], v[210:211], v[240:241]
	v_cvt_pk_bf16_f32 v185, v234, v235
	v_cvt_pk_bf16_f32 v193, v240, v241
	v_mov_b32_dpp v250, v14 row_shr:1 row_mask:0xf bank_mask:0xf bound_ctrl:1
	v_mov_b32_dpp v251, v15 row_shr:1 row_mask:0xf bank_mask:0xf bound_ctrl:1
	v_mov_b32_dpp v252, v78 row_shl:1 row_mask:0xf bank_mask:0xf bound_ctrl:1
	v_mov_b32_dpp v253, v79 row_shl:1 row_mask:0xf bank_mask:0xf bound_ctrl:1
	v_pk_fma_f32 v[242:243], v[78:79], v[208:209], v[216:217]
	v_pk_fma_f32 v[244:245], v[46:47], v[208:209], v[216:217]
	v_pk_fma_f32 v[246:247], v[30:31], v[208:209], v[216:217]
	v_pk_fma_f32 v[248:249], v[14:15], v[208:209], v[216:217]
	v_pk_fma_f32 v[242:243], v[250:251], v[204:205], v[242:243]
	v_pk_fma_f32 v[244:245], v[78:79], v[204:205], v[244:245]
	v_pk_fma_f32 v[246:247], v[46:47], v[204:205], v[246:247]
	v_pk_fma_f32 v[248:249], v[30:31], v[204:205], v[248:249]
	v_pk_fma_f32 v[242:243], v[46:47], v[212:213], v[242:243]
	v_pk_fma_f32 v[244:245], v[30:31], v[212:213], v[244:245]
	v_pk_fma_f32 v[246:247], v[14:15], v[212:213], v[246:247]
	v_pk_fma_f32 v[248:249], v[252:253], v[212:213], v[248:249]
	v_cvt_pk_bf16_f32 v189, v242, v243
	v_cvt_pk_bf16_f32 v155, v248, v249
	ds_read_b64 v[202:203], v132 offset:16
	ds_read_b64 v[204:205], v132 offset:144
	ds_read_b64 v[206:207], v132 offset:272
	ds_read_b64 v[208:209], v132 offset:400
	ds_read_b64 v[210:211], v132 offset:528
	ds_read_b64 v[212:213], v132 offset:656
	ds_read_b64 v[214:215], v132 offset:784
	ds_read_b64 v[216:217], v132 offset:912
	v_pk_mul_f32 v[138:139], v[234:235], v[234:235]
	v_pk_mul_f32 v[140:141], v[236:237], v[236:237]
	v_pk_mul_f32 v[142:143], v[238:239], v[238:239]
	v_pk_mul_f32 v[144:145], v[240:241], v[240:241]
	v_pk_fma_f32 v[138:139], v[138:139], v[134:135], v[136:137]
	v_pk_fma_f32 v[140:141], v[140:141], v[134:135], v[136:137]
	v_pk_fma_f32 v[142:143], v[142:143], v[134:135], v[136:137]
	v_pk_fma_f32 v[144:145], v[144:145], v[134:135], v[136:137]
	v_pk_mul_f32 v[138:139], v[234:235], v[138:139]
	v_pk_mul_f32 v[140:141], v[236:237], v[140:141]
	v_pk_mul_f32 v[142:143], v[238:239], v[142:143]
	v_pk_mul_f32 v[144:145], v[240:241], v[144:145]
	v_exp_f32_e32 v138, v138
	v_exp_f32_e32 v139, v139
	v_exp_f32_e32 v140, v140
	v_exp_f32_e32 v141, v141
	v_exp_f32_e32 v142, v142
	v_exp_f32_e32 v143, v143
	v_exp_f32_e32 v144, v144
	v_exp_f32_e32 v145, v145
	v_pk_mul_f32 v[146:147], v[234:235], v[242:243]
	v_pk_mul_f32 v[148:149], v[236:237], v[244:245]
	v_pk_mul_f32 v[150:151], v[238:239], v[246:247]
	v_pk_mul_f32 v[152:153], v[240:241], v[248:249]
	v_pk_add_f32 v[138:139], v[138:139], 1.0 op_sel_hi:[1,0]
	v_pk_add_f32 v[140:141], v[140:141], 1.0 op_sel_hi:[1,0]
	v_pk_add_f32 v[142:143], v[142:143], 1.0 op_sel_hi:[1,0]
	v_pk_add_f32 v[144:145], v[144:145], 1.0 op_sel_hi:[1,0]
	v_rcp_f32_e32 v138, v138
	v_rcp_f32_e32 v139, v139
	v_rcp_f32_e32 v140, v140
	v_rcp_f32_e32 v141, v141
	v_rcp_f32_e32 v142, v142
	v_rcp_f32_e32 v143, v143
	v_rcp_f32_e32 v144, v144
	v_rcp_f32_e32 v145, v145
	v_pk_mul_f32 v[146:147], v[146:147], v[138:139]
	v_pk_mul_f32 v[148:149], v[148:149], v[140:141]
	v_pk_mul_f32 v[150:151], v[150:151], v[142:143]
	v_pk_mul_f32 v[152:153], v[152:153], v[144:145]
	v_cvt_pk_bf16_f32 v219, v146, v147
	v_cvt_pk_bf16_f32 v223, v148, v149
	v_cvt_pk_bf16_f32 v227, v150, v151
	v_cvt_pk_bf16_f32 v231, v152, v153
	s_waitcnt lgkmcnt(0)
;     __device__ __forceinline__ void operator()(const f32x4 (&acc)[2][2][4][2], const Unit& u) const {
;     ...
;                     for (int ep = 0; ep < 2; ++ep) {
;                         f32x2 cres[2][4];
; #pragma unroll
;                         for (int part = 0; part < 2; ++part) {
;                             const f32x2 w0 = (f32x2){W[part][0][2 * ep], W[part][0][2 * ep + 1]}, w1 = (f32x2){W[part][1][2 * ep], W[part][1][2 * ep + 1]};
;                             const f32x2 w2 = (f32x2){W[part][2][2 * ep], W[part][2][2 * ep + 1]}, bb = (f32x2){W[part][3][2 * ep], W[part][3][2 * ep + 1]};
;                             const f32x2 w0a = w0 * n0, w0b = w0 * m0, w2a = w2 * n15, w2b = w2 * m15;
;                             f32x2 X[4], R[4], L[4];
; #pragma unroll
;                             for (int m = 0; m < 4; ++m) { X[m] = (f32x2){acc[ai][part][m][n][2 * ep], acc[ai][part][m][n][2 * ep + 1]};
;                                 R[m] = (f32x2){dpp_prev(X[m].x), dpp_prev(X[m].y)}; L[m] = (f32x2){dpp_next(X[m].x), dpp_next(X[m].y)}; }
; #pragma unroll
;                             for (int m = 0; m < 4; ++m) {
;                                 f32x2 c = X[m] * w1 + bb; c = R[m] * w0a + c; c = L[m] * w2a + c;
;                                 if (m > 0) c = R[m > 0 ? m - 1 : 0] * w0b + c;
;                                 if (m < 3) c = L[m < 3 ? m + 1 : 3] * w2b + c;
;                                 cres[part][m] = c;
;                             }
;                             pe[0][part][n * 2 + ep] = cvt_pk_bf16(cres[part][0].x, cres[part][0].y);
;                             pe[1][part][n * 2 + ep] = cvt_pk_bf16(cres[part][3].x, cres[part][3].y);
;                             __builtin_amdgcn_sched_barrier(0);
;                         }
; #pragma unroll
;                         for (int m = 0; m < 4; ++m) {
;                             const f32x2 a = cres[0][m], v = cres[1][m];
;                             const f32x2 t = (a * a) * (-0.10294324f) + (-2.3022082f), z = a * t;
;                             f32x2 d; d.x = __builtin_amdgcn_exp2f(z.x) + 1.f; d.y = __builtin_amdgcn_exp2f(z.y) + 1.f;
;                             f32x2 r; r.x = __builtin_amdgcn_rcpf(d.x); r.y = __builtin_amdgcn_rcpf(d.y);
;                             const f32x2 o = (a * v) * r;
;                             gq[m][n * 2 + ep] = cvt_pk_bf16(o.x, o.y);
	v_mov_b32_dpp v250, v0 row_shr:1 row_mask:0xf bank_mask:0xf bound_ctrl:1
	v_mov_b32_dpp v251, v1 row_shr:1 row_mask:0xf bank_mask:0xf bound_ctrl:1
	v_mov_b32_dpp v252, v56 row_shl:1 row_mask:0xf bank_mask:0xf bound_ctrl:1
	v_mov_b32_dpp v253, v57 row_shl:1 row_mask:0xf bank_mask:0xf bound_ctrl:1
	v_pk_fma_f32 v[234:235], v[56:57], v[206:207], v[214:215]
	v_pk_fma_f32 v[236:237], v[32:33], v[206:207], v[214:215]
	v_pk_fma_f32 v[238:239], v[16:17], v[206:207], v[214:215]
	v_pk_fma_f32 v[240:241], v[0:1], v[206:207], v[214:215]
	v_pk_fma_f32 v[234:235], v[250:251], v[202:203], v[234:235]
	v_pk_fma_f32 v[236:237], v[56:57], v[202:203], v[236:237]
	v_pk_fma_f32 v[238:239], v[32:33], v[202:203], v[238:239]
	v_pk_fma_f32 v[240:241], v[16:17], v[202:203], v[240:241]
	v_pk_fma_f32 v[234:235], v[32:33], v[210:211], v[234:235]
	v_pk_fma_f32 v[236:237], v[16:17], v[210:211], v[236:237]
	v_pk_fma_f32 v[238:239], v[0:1], v[210:211], v[238:239]
	v_pk_fma_f32 v[240:241], v[252:253], v[210:211], v[240:241]
	v_cvt_pk_bf16_f32 v186, v234, v235
	v_cvt_pk_bf16_f32 v194, v240, v241
	v_mov_b32_dpp v250, v8 row_shr:1 row_mask:0xf bank_mask:0xf bound_ctrl:1
	v_mov_b32_dpp v251, v9 row_shr:1 row_mask:0xf bank_mask:0xf bound_ctrl:1
	v_mov_b32_dpp v252, v72 row_shl:1 row_mask:0xf bank_mask:0xf bound_ctrl:1
	v_mov_b32_dpp v253, v73 row_shl:1 row_mask:0xf bank_mask:0xf bound_ctrl:1
	v_pk_fma_f32 v[242:243], v[72:73], v[208:209], v[216:217]
	v_pk_fma_f32 v[244:245], v[40:41], v[208:209], v[216:217]
	v_pk_fma_f32 v[246:247], v[24:25], v[208:209], v[216:217]
	v_pk_fma_f32 v[248:249], v[8:9], v[208:209], v[216:217]
	v_pk_fma_f32 v[242:243], v[250:251], v[204:205], v[242:243]
	v_pk_fma_f32 v[244:245], v[72:73], v[204:205], v[244:245]
	v_pk_fma_f32 v[246:247], v[40:41], v[204:205], v[246:247]
	v_pk_fma_f32 v[248:249], v[24:25], v[204:205], v[248:249]
	v_pk_fma_f32 v[242:243], v[40:41], v[212:213], v[242:243]
	v_pk_fma_f32 v[244:245], v[24:25], v[212:213], v[244:245]
	v_pk_fma_f32 v[246:247], v[8:9], v[212:213], v[246:247]
	v_pk_fma_f32 v[248:249], v[252:253], v[212:213], v[248:249]
	v_cvt_pk_bf16_f32 v190, v242, v243
	v_cvt_pk_bf16_f32 v156, v248, v249
	ds_read_b64 v[202:203], v132 offset:24
	ds_read_b64 v[204:205], v132 offset:152
	ds_read_b64 v[206:207], v132 offset:280
	ds_read_b64 v[208:209], v132 offset:408
	ds_read_b64 v[210:211], v132 offset:536
	ds_read_b64 v[212:213], v132 offset:664
	ds_read_b64 v[214:215], v132 offset:792
	ds_read_b64 v[216:217], v132 offset:920
	v_pk_mul_f32 v[138:139], v[234:235], v[234:235]
	v_pk_mul_f32 v[140:141], v[236:237], v[236:237]
	v_pk_mul_f32 v[142:143], v[238:239], v[238:239]
	v_pk_mul_f32 v[144:145], v[240:241], v[240:241]
	v_pk_fma_f32 v[138:139], v[138:139], v[134:135], v[136:137]
	v_pk_fma_f32 v[140:141], v[140:141], v[134:135], v[136:137]
	v_pk_fma_f32 v[142:143], v[142:143], v[134:135], v[136:137]
	v_pk_fma_f32 v[144:145], v[144:145], v[134:135], v[136:137]
	v_pk_mul_f32 v[138:139], v[234:235], v[138:139]
	v_pk_mul_f32 v[140:141], v[236:237], v[140:141]
	v_pk_mul_f32 v[142:143], v[238:239], v[142:143]
	v_pk_mul_f32 v[144:145], v[240:241], v[144:145]
	v_exp_f32_e32 v138, v138
	v_exp_f32_e32 v139, v139
	v_exp_f32_e32 v140, v140
	v_exp_f32_e32 v141, v141
	v_exp_f32_e32 v142, v142
	v_exp_f32_e32 v143, v143
	v_exp_f32_e32 v144, v144
	v_exp_f32_e32 v145, v145
	v_pk_mul_f32 v[146:147], v[234:235], v[242:243]
	v_pk_mul_f32 v[148:149], v[236:237], v[244:245]
	v_pk_mul_f32 v[150:151], v[238:239], v[246:247]
	v_pk_mul_f32 v[152:153], v[240:241], v[248:249]
	v_pk_add_f32 v[138:139], v[138:139], 1.0 op_sel_hi:[1,0]
	v_pk_add_f32 v[140:141], v[140:141], 1.0 op_sel_hi:[1,0]
	v_pk_add_f32 v[142:143], v[142:143], 1.0 op_sel_hi:[1,0]
	v_pk_add_f32 v[144:145], v[144:145], 1.0 op_sel_hi:[1,0]
	v_rcp_f32_e32 v138, v138
	v_rcp_f32_e32 v139, v139
	v_rcp_f32_e32 v140, v140
	v_rcp_f32_e32 v141, v141
	v_rcp_f32_e32 v142, v142
	v_rcp_f32_e32 v143, v143
	v_rcp_f32_e32 v144, v144
	v_rcp_f32_e32 v145, v145
	v_pk_mul_f32 v[146:147], v[146:147], v[138:139]
	v_pk_mul_f32 v[148:149], v[148:149], v[140:141]
	v_pk_mul_f32 v[150:151], v[150:151], v[142:143]
	v_pk_mul_f32 v[152:153], v[152:153], v[144:145]
	v_cvt_pk_bf16_f32 v220, v146, v147
	v_cvt_pk_bf16_f32 v224, v148, v149
	v_cvt_pk_bf16_f32 v228, v150, v151
	v_cvt_pk_bf16_f32 v232, v152, v153
	s_waitcnt lgkmcnt(0)
;     __device__ __forceinline__ void operator()(const f32x4 (&acc)[2][2][4][2], const Unit& u) const {
;     ...
;                     for (int ep = 0; ep < 2; ++ep) {
;                         f32x2 cres[2][4];
; #pragma unroll
;                         for (int part = 0; part < 2; ++part) {
;                             const f32x2 w0 = (f32x2){W[part][0][2 * ep], W[part][0][2 * ep + 1]}, w1 = (f32x2){W[part][1][2 * ep], W[part][1][2 * ep + 1]};
;                             const f32x2 w2 = (f32x2){W[part][2][2 * ep], W[part][2][2 * ep + 1]}, bb = (f32x2){W[part][3][2 * ep], W[part][3][2 * ep + 1]};
;                             const f32x2 w0a = w0 * n0, w0b = w0 * m0, w2a = w2 * n15, w2b = w2 * m15;
;                             f32x2 X[4], R[4], L[4];
; #pragma unroll
;                             for (int m = 0; m < 4; ++m) { X[m] = (f32x2){acc[ai][part][m][n][2 * ep], acc[ai][part][m][n][2 * ep + 1]};
;                                 R[m] = (f32x2){dpp_prev(X[m].x), dpp_prev(X[m].y)}; L[m] = (f32x2){dpp_next(X[m].x), dpp_next(X[m].y)}; }
; #pragma unroll
;                             for (int m = 0; m < 4; ++m) {
;                                 f32x2 c = X[m] * w1 + bb; c = R[m] * w0a + c; c = L[m] * w2a + c;
;                                 if (m > 0) c = R[m > 0 ? m - 1 : 0] * w0b + c;
;                                 if (m < 3) c = L[m < 3 ? m + 1 : 3] * w2b + c;
;                                 cres[part][m] = c;
;                             }
;                             pe[0][part][n * 2 + ep] = cvt_pk_bf16(cres[part][0].x, cres[part][0].y);
;                             pe[1][part][n * 2 + ep] = cvt_pk_bf16(cres[part][3].x, cres[part][3].y);
;                             __builtin_amdgcn_sched_barrier(0);
;                         }
; #pragma unroll
;                         for (int m = 0; m < 4; ++m) {
;                             const f32x2 a = cres[0][m], v = cres[1][m];
;                             const f32x2 t = (a * a) * (-0.10294324f) + (-2.3022082f), z = a * t;
;                             f32x2 d; d.x = __builtin_amdgcn_exp2f(z.x) + 1.f; d.y = __builtin_amdgcn_exp2f(z.y) + 1.f;
;                             f32x2 r; r.x = __builtin_amdgcn_rcpf(d.x); r.y = __builtin_amdgcn_rcpf(d.y);
;                             const f32x2 o = (a * v) * r;
;                             gq[m][n * 2 + ep] = cvt_pk_bf16(o.x, o.y);
	v_mov_b32_dpp v250, v2 row_shr:1 row_mask:0xf bank_mask:0xf bound_ctrl:1
	v_mov_b32_dpp v251, v3 row_shr:1 row_mask:0xf bank_mask:0xf bound_ctrl:1
	v_mov_b32_dpp v252, v58 row_shl:1 row_mask:0xf bank_mask:0xf bound_ctrl:1
	v_mov_b32_dpp v253, v59 row_shl:1 row_mask:0xf bank_mask:0xf bound_ctrl:1
	v_pk_fma_f32 v[234:235], v[58:59], v[206:207], v[214:215]
	v_pk_fma_f32 v[236:237], v[34:35], v[206:207], v[214:215]
	v_pk_fma_f32 v[238:239], v[18:19], v[206:207], v[214:215]
	v_pk_fma_f32 v[240:241], v[2:3], v[206:207], v[214:215]
	v_pk_fma_f32 v[234:235], v[250:251], v[202:203], v[234:235]
	v_pk_fma_f32 v[236:237], v[58:59], v[202:203], v[236:237]
	v_pk_fma_f32 v[238:239], v[34:35], v[202:203], v[238:239]
	v_pk_fma_f32 v[240:241], v[18:19], v[202:203], v[240:241]
	v_pk_fma_f32 v[234:235], v[34:35], v[210:211], v[234:235]
	v_pk_fma_f32 v[236:237], v[18:19], v[210:211], v[236:237]
	v_pk_fma_f32 v[238:239], v[2:3], v[210:211], v[238:239]
	v_pk_fma_f32 v[240:241], v[252:253], v[210:211], v[240:241]
	v_cvt_pk_bf16_f32 v187, v234, v235
	v_cvt_pk_bf16_f32 v195, v240, v241
	v_mov_b32_dpp v250, v10 row_shr:1 row_mask:0xf bank_mask:0xf bound_ctrl:1
	v_mov_b32_dpp v251, v11 row_shr:1 row_mask:0xf bank_mask:0xf bound_ctrl:1
	v_mov_b32_dpp v252, v74 row_shl:1 row_mask:0xf bank_mask:0xf bound_ctrl:1
	v_mov_b32_dpp v253, v75 row_shl:1 row_mask:0xf bank_mask:0xf bound_ctrl:1
	v_pk_fma_f32 v[242:243], v[74:75], v[208:209], v[216:217]
	v_pk_fma_f32 v[244:245], v[42:43], v[208:209], v[216:217]
	v_pk_fma_f32 v[246:247], v[26:27], v[208:209], v[216:217]
	v_pk_fma_f32 v[248:249], v[10:11], v[208:209], v[216:217]
	v_pk_fma_f32 v[242:243], v[250:251], v[204:205], v[242:243]
	v_pk_fma_f32 v[244:245], v[74:75], v[204:205], v[244:245]
	v_pk_fma_f32 v[246:247], v[42:43], v[204:205], v[246:247]
	v_pk_fma_f32 v[248:249], v[26:27], v[204:205], v[248:249]
	v_pk_fma_f32 v[242:243], v[42:43], v[212:213], v[242:243]
	v_pk_fma_f32 v[244:245], v[26:27], v[212:213], v[244:245]
	v_pk_fma_f32 v[246:247], v[10:11], v[212:213], v[246:247]
	v_pk_fma_f32 v[248:249], v[252:253], v[212:213], v[248:249]
	v_cvt_pk_bf16_f32 v191, v242, v243
	v_cvt_pk_bf16_f32 v157, v248, v249
	v_pk_mul_f32 v[138:139], v[234:235], v[234:235]
	v_pk_mul_f32 v[140:141], v[236:237], v[236:237]
	v_pk_mul_f32 v[142:143], v[238:239], v[238:239]
	v_pk_mul_f32 v[144:145], v[240:241], v[240:241]
	v_pk_fma_f32 v[138:139], v[138:139], v[134:135], v[136:137]
	v_pk_fma_f32 v[140:141], v[140:141], v[134:135], v[136:137]
	v_pk_fma_f32 v[142:143], v[142:143], v[134:135], v[136:137]
	v_pk_fma_f32 v[144:145], v[144:145], v[134:135], v[136:137]
	v_pk_mul_f32 v[138:139], v[234:235], v[138:139]
	v_pk_mul_f32 v[140:141], v[236:237], v[140:141]
	v_pk_mul_f32 v[142:143], v[238:239], v[142:143]
	v_pk_mul_f32 v[144:145], v[240:241], v[144:145]
	v_exp_f32_e32 v138, v138
	v_exp_f32_e32 v139, v139
	v_exp_f32_e32 v140, v140
	v_exp_f32_e32 v141, v141
	v_exp_f32_e32 v142, v142
	v_exp_f32_e32 v143, v143
	v_exp_f32_e32 v144, v144
	v_exp_f32_e32 v145, v145
	v_pk_mul_f32 v[146:147], v[234:235], v[242:243]
	v_pk_mul_f32 v[148:149], v[236:237], v[244:245]
	v_pk_mul_f32 v[150:151], v[238:239], v[246:247]
	v_pk_mul_f32 v[152:153], v[240:241], v[248:249]
	v_pk_add_f32 v[138:139], v[138:139], 1.0 op_sel_hi:[1,0]
	v_pk_add_f32 v[140:141], v[140:141], 1.0 op_sel_hi:[1,0]
	v_pk_add_f32 v[142:143], v[142:143], 1.0 op_sel_hi:[1,0]
	v_pk_add_f32 v[144:145], v[144:145], 1.0 op_sel_hi:[1,0]
	v_rcp_f32_e32 v138, v138
	v_rcp_f32_e32 v139, v139
	v_rcp_f32_e32 v140, v140
	v_rcp_f32_e32 v141, v141
	v_rcp_f32_e32 v142, v142
	v_rcp_f32_e32 v143, v143
	v_rcp_f32_e32 v144, v144
	v_rcp_f32_e32 v145, v145
	v_pk_mul_f32 v[146:147], v[146:147], v[138:139]
	v_pk_mul_f32 v[148:149], v[148:149], v[140:141]
	v_pk_mul_f32 v[150:151], v[150:151], v[142:143]
	v_pk_mul_f32 v[152:153], v[152:153], v[144:145]
	v_cvt_pk_bf16_f32 v221, v146, v147
	v_cvt_pk_bf16_f32 v225, v148, v149
	v_cvt_pk_bf16_f32 v229, v150, v151
	v_cvt_pk_bf16_f32 v233, v152, v153
	s_mov_b64 s[22:23], exec
	s_mov_b64 exec, s[6:7]
	v_cvt_pk_bf16_f32 v138, v64, v65
	v_cvt_pk_bf16_f32 v139, v66, v67
	v_cvt_pk_bf16_f32 v140, v56, v57
	v_cvt_pk_bf16_f32 v141, v58, v59
	v_cvt_pk_bf16_f32 v142, v76, v77
	v_cvt_pk_bf16_f32 v143, v78, v79
	v_cvt_pk_bf16_f32 v144, v72, v73
	v_cvt_pk_bf16_f32 v145, v74, v75
	global_store_dwordx4 v129, v[138:141], s[10:11]
	global_store_dwordx4 v129, v[142:145], s[10:11] offset:16
	global_store_dwordx4 v129, v[184:187], s[10:11] offset:32
	global_store_dwordx4 v129, v[188:191], s[10:11] offset:48
	s_mov_b64 exec, s[8:9]
	v_cvt_pk_bf16_f32 v146, v4, v5
	v_cvt_pk_bf16_f32 v147, v6, v7
	v_cvt_pk_bf16_f32 v148, v0, v1
	v_cvt_pk_bf16_f32 v149, v2, v3
	v_cvt_pk_bf16_f32 v150, v12, v13
	v_cvt_pk_bf16_f32 v151, v14, v15
	v_cvt_pk_bf16_f32 v152, v8, v9
	v_cvt_pk_bf16_f32 v153, v10, v11
	global_store_dwordx4 v162, v[146:149], s[10:11]
	global_store_dwordx4 v162, v[150:153], s[10:11] offset:16
	global_store_dwordx4 v162, v[192:195], s[10:11] offset:32
	global_store_dwordx4 v162, v[154:157], s[10:11] offset:48
	s_mov_b64 exec, s[56:57]
	global_store_dwordx4 v128, v[218:221], s[52:53]
	s_mov_b64 exec, s[22:23]
	v_add_u32_e32 v133, 0x1600, v128
	v_add_u32_e32 v130, 0x2c00, v128
	v_add_u32_e32 v131, 0x4200, v128
	global_store_dwordx4 v133, v[222:225], s[52:53]
	global_store_dwordx4 v130, v[226:229], s[52:53]
	s_mov_b64 exec, s[58:59]
	global_store_dwordx4 v131, v[230:233], s[52:53]
	s_mov_b64 exec, s[22:23]
	s_mov_b64 s[8:9], 0
